# attention: s_setprio 1 during the MFMA (X) phase of each wave half, 0 in the softmax phase; O1 reloads in two bursts
# baseline (speedup 1.0000x reference)
; #define LAS __attribute__((address_space(3)))
; __device__ __forceinline__ float qkt(f32x16& p0, f32x16& p1, const LAS char* Ks, const bf16x8* qr, int r32, int hi, int dlt, float cL, float cR, const LAS float* tabL) {
;     bf16x8 b0[4], b1[4];
; #pragma unroll
;     for (int d0 = 0; d0 < 4; ++d0) { const int cb = d0 * 32 + hi * 16;
;         b0[d0] = *(const LAS bf16x8*)(Ks + KSWZ64(r32, cb)); b1[d0] = *(const LAS bf16x8*)(Ks + KSWZ64(32 + r32, cb)); }
;     if (dlt <= -191 || dlt >= 159) {
;         const f32x16 z = f32x16{};
;         p0 = __builtin_amdgcn_mfma_f32_32x32x16_bf16(b0[0], qr[0], z, 0, 0, 0); p1 = __builtin_amdgcn_mfma_f32_32x32x16_bf16(b1[0], qr[0], z, 0, 0, 0);
; #pragma unroll
;         for (int d0 = 1; d0 < 4; ++d0) { p0 = __builtin_amdgcn_mfma_f32_32x32x16_bf16(b0[d0], qr[d0], p0, 0, 0, 0); p1 = __builtin_amdgcn_mfma_f32_32x32x16_bf16(b1[d0], qr[d0], p1, 0, 0, 0); }
;         return dlt < 0 ? cL : cR;
;     }
.Lat_enter:
	s_setprio 1
	s_add_i32 s24, s40, 2
	s_and_b32 s24, s24, 3
	s_lshl_b32 s12, s24, 13
	s_add_i32 s12, s12, s66
	s_lshl_b32 s13, s24, 14
	s_add_i32 s13, s13, s74
	s_add_i32 m0, s12, 0x14000
	s_nop 0
	global_load_lds_dwordx4 v[204:205], off
	s_mov_b32 m0, s13
	v_lshl_add_u64 v[204:205], v[204:205], 0, s[6:7]
	global_load_lds_dwordx4 v[250:251], off
	s_add_i32 m0, s13, 0x400
	v_lshl_add_u64 v[250:251], v[250:251], 0, s[6:7]
	global_load_lds_dwordx4 v[246:247], off
	v_lshl_add_u64 v[246:247], v[246:247], 0, s[6:7]
	s_and_b32 s41, s40, 3
	s_lshl_b32 s41, s41, 13
	v_add_u32_e32 v244, s41, v239
	v_add_u32_e32 v249, s41, v240
	v_add_u32_e32 v212, s41, v241
	v_add_u32_e32 v248, s41, v242
	ds_read_b128 v[98:101], v244
	ds_read_b128 v[102:105], v244 offset:4096
	ds_read_b128 v[106:109], v249
	ds_read_b128 v[110:113], v249 offset:4096
	ds_read_b128 v[114:117], v212
	ds_read_b128 v[118:121], v212 offset:4096
	ds_read_b128 v[122:125], v248
	ds_read_b128 v[126:129], v248 offset:4096
	s_add_i32 s12, s65, 190
	s_cmp_lt_u32 s12, 349
	s_cbranch_scc1 .Lat_near_p
	s_cmp_lt_i32 s65, 0
	s_cselect_b64 vcc, -1, 0
	v_cndmask_b32_e32 v0, v224, v223, vcc
	s_waitcnt lgkmcnt(0)
	v_mfma_f32_32x32x16_bf16 v[82:97], v[98:101], v[142:145], 0
	v_mfma_f32_32x32x16_bf16 v[66:81], v[102:105], v[142:145], 0
	v_mfma_f32_32x32x16_bf16 v[82:97], v[106:109], v[138:141], v[82:97]
	v_mfma_f32_32x32x16_bf16 v[66:81], v[110:113], v[138:141], v[66:81]
	v_mfma_f32_32x32x16_bf16 v[82:97], v[114:117], v[134:137], v[82:97]
	v_mfma_f32_32x32x16_bf16 v[66:81], v[118:121], v[134:137], v[66:81]
	v_mfma_f32_32x32x16_bf16 v[82:97], v[122:125], v[130:133], v[82:97]
	v_mfma_f32_32x32x16_bf16 v[66:81], v[126:129], v[130:133], v[66:81]
	s_branch .Lat_qkd_p

; #define MX3(a, b, c) __builtin_fmaxf(__builtin_fmaxf((a), (b)), (c))
; __device__ __forceinline__ void partialSM(f32x16& p0, f32x16& p1, float& m_reg, float& mn, float& alpha, float boff) {
;     constexpr float C = SCALE * 1.4426950408889634f;
;     float a = MX3(p0[0], p0[1], p1[0]), b = MX3(p0[2], p0[3], p1[1]); a = MX3(a, p1[2], p1[3]);
; #pragma unroll
;     for (int r = 4; r < 16; r += 4) { a = MX3(a, p0[r], p0[r + 1]); b = MX3(b, p0[r + 2], p0[r + 3]); a = MX3(a, p1[r], p1[r + 1]); b = MX3(b, p1[r + 2], p1[r + 3]); }
;     float pmax = __builtin_fmaxf(a, b);
;     { auto rr = __builtin_amdgcn_permlane32_swap(__float_as_uint(pmax), __float_as_uint(pmax), false, false);
;       pmax = fmaxf(__uint_as_float(rr[0]), __uint_as_float(rr[1])) + boff; }
;     if (__builtin_expect(__all(pmax - m_reg <= THR / SCALE), 1)) { mn = m_reg; alpha = 1.f; }
;     else { mn = fmaxf(m_reg, pmax); alpha = __builtin_amdgcn_exp2f((m_reg - mn) * C); m_reg = mn; }
.Lat_qkd_p:
	s_nop 15
	s_setprio 0
	s_waitcnt vmcnt(3)
	s_barrier
	v_max_f32_e32 v244, v83, v83
	v_max_f32_e32 v249, v82, v82
	v_max_f32_e32 v244, v249, v244
	v_max3_f32 v249, v84, v85, v67
	v_max3_f32 v244, v244, v66, v68
	v_max3_f32 v244, v244, v69, v86
	v_max3_f32 v249, v249, v88, v89
	v_max3_f32 v244, v244, v87, v70
	v_max3_f32 v249, v249, v72, v73
	v_max3_f32 v244, v244, v71, v90
	v_max3_f32 v249, v249, v92, v93
	v_max3_f32 v244, v244, v91, v74
	v_max3_f32 v249, v249, v76, v77
	v_max3_f32 v244, v244, v75, v94
	v_max3_f32 v249, v249, v96, v97
	v_max3_f32 v244, v244, v95, v78
	v_max3_f32 v249, v249, v80, v81
	v_max3_f32 v244, v244, v79, v249
	v_mov_b32_e32 v249, v244
	s_nop 1
	v_permlane32_swap_b32_e32 v244, v249
	v_max_f32_e32 v249, v249, v249
	v_max_f32_e32 v244, v244, v244
	v_max_f32_e32 v244, v244, v249
	v_add_f32_e32 v244, v0, v244
	v_sub_f32_e32 v249, v244, v243
	v_cmp_ge_f32_e32 vcc, s72, v249
	v_max_f32_e32 v249, v243, v243
	v_max_f32_e32 v249, v249, v244
	v_sub_f32_e32 v212, v243, v249
	v_mul_f32_e32 v212, 0x3e38aa3b, v212
	v_exp_f32_e32 v212, v212
	s_cmp_eq_u64 vcc, exec
	s_cselect_b64 s[0:1], -1, 0
	v_cndmask_b32_e64 v248, v212, 1.0, s[0:1]
	v_cmp_gt_f32_e32 vcc, 1.0, v248
	s_cbranch_vccz .Lat_noresc_p
	s_and_saveexec_b64 s[12:13], s[38:39]
	ds_write_b32 v232, v248 offset:128
	s_or_b64 exec, exec, s[12:13]
	s_waitcnt lgkmcnt(0)
	v_add_u32_e32 v110, s31, v188
	ds_read_b128 v[98:101], v110 offset:224
	ds_read_b128 v[102:105], v110 offset:192
	ds_read_b128 v[106:109], v110 offset:160
	ds_read_b128 v[110:113], v110 offset:128
	s_waitcnt lgkmcnt(0)
	v_pk_mul_f32 v[62:63], v[62:63], v[98:99]
	v_pk_mul_f32 v[58:59], v[58:59], v[102:103]
	v_pk_mul_f32 v[54:55], v[54:55], v[106:107]
	v_pk_mul_f32 v[64:65], v[64:65], v[100:101]
	v_pk_mul_f32 v[60:61], v[60:61], v[104:105]
	v_pk_mul_f32 v[56:57], v[56:57], v[108:109]
	v_pk_mul_f32 v[52:53], v[52:53], v[112:113]
	v_pk_mul_f32 v[50:51], v[50:51], v[110:111]
	v_pk_mul_f32 v[46:47], v[46:47], v[98:99]
	v_pk_mul_f32 v[42:43], v[42:43], v[102:103]
	v_pk_mul_f32 v[38:39], v[38:39], v[106:107]
	v_pk_mul_f32 v[48:49], v[48:49], v[100:101]
	v_pk_mul_f32 v[44:45], v[44:45], v[104:105]
	v_pk_mul_f32 v[40:41], v[40:41], v[108:109]
	v_pk_mul_f32 v[36:37], v[36:37], v[112:113]
	v_pk_mul_f32 v[34:35], v[34:35], v[110:111]
	v_pk_mul_f32 v[30:31], v[30:31], v[98:99]
	v_pk_mul_f32 v[26:27], v[26:27], v[102:103]
	v_pk_mul_f32 v[22:23], v[22:23], v[106:107]
	v_pk_mul_f32 v[32:33], v[32:33], v[100:101]
	v_pk_mul_f32 v[28:29], v[28:29], v[104:105]
	v_pk_mul_f32 v[24:25], v[24:25], v[108:109]
	v_pk_mul_f32 v[20:21], v[20:21], v[112:113]
	v_pk_mul_f32 v[18:19], v[18:19], v[110:111]
	v_pk_mul_f32 v[14:15], v[14:15], v[98:99]
	v_pk_mul_f32 v[10:11], v[10:11], v[102:103]
	v_pk_mul_f32 v[6:7], v[6:7], v[106:107]
	v_pk_mul_f32 v[16:17], v[16:17], v[100:101]
	v_pk_mul_f32 v[12:13], v[12:13], v[104:105]
	v_pk_mul_f32 v[8:9], v[8:9], v[108:109]
	v_pk_mul_f32 v[4:5], v[4:5], v[112:113]
	v_pk_mul_f32 v[2:3], v[2:3], v[110:111]

; #define WAITBAR(N) asm volatile("s_waitcnt vmcnt(" #N ") lgkmcnt(0)\n\ts_barrier" ::: "memory")
; __device__ __forceinline__ void attn_unit(int b, int h, int qb, const bf16_t* __restrict__ proj, const float* __restrict__ btab, float lam, float outscale,
;                                           const float* __restrict__ gain, float* o1scr, bf16_t* merged, LAS char* lds) {
;     ...
; #pragma unroll 1
;         for (int j = 1; j + 1 < NT; j += 2) {
;             WAITBAR(0);
;             DMA_TILE(j + 1, bn);
.Lat_loop:
	s_setprio 1
	s_cmp_gt_u32 s40, 61
	s_cbranch_scc1 .Lat_nodma_l
	s_add_i32 s24, s40, 2
	s_and_b32 s24, s24, 3
	s_lshl_b32 s12, s24, 13
	s_add_i32 s12, s12, s66
	s_lshl_b32 s13, s24, 14
	s_add_i32 s13, s13, s74
	s_add_i32 m0, s12, 0x14000
	s_nop 0
	global_load_lds_dwordx4 v[204:205], off
	s_mov_b32 m0, s13
	v_lshl_add_u64 v[204:205], v[204:205], 0, s[6:7]
	global_load_lds_dwordx4 v[250:251], off
	s_add_i32 m0, s13, 0x400
	v_lshl_add_u64 v[250:251], v[250:251], 0, s[6:7]
	global_load_lds_dwordx4 v[246:247], off
	v_lshl_add_u64 v[246:247], v[246:247], 0, s[6:7]

; #define SBAR() __builtin_amdgcn_sched_barrier(0)
; template <int D0> __device__ __forceinline__ void pv_one(f32x16& od, int vb, bf16x8 pa0, bf16x8 pa1, bf16x8 pa2, bf16x8 pa3) {
;     const s16x4 l0 = tr_read<v_rd_off(D0, 0, 0)>(vb), h0 = tr_read<v_rd_off(D0, 0, 1)>(vb), l1 = tr_read<v_rd_off(D0, 1, 0)>(vb), h1 = tr_read<v_rd_off(D0, 1, 1)>(vb);
;     const s16x4 l2 = tr_read<v_rd_off(D0, 2, 0)>(vb), h2 = tr_read<v_rd_off(D0, 2, 1)>(vb), l3 = tr_read<v_rd_off(D0, 3, 0)>(vb), h3 = tr_read<v_rd_off(D0, 3, 1)>(vb);
;     asm volatile("s_waitcnt lgkmcnt(0)" ::: "memory"); SBAR();
;     ...
;     od = __builtin_amdgcn_mfma_f32_32x32x16_bf16(pa0, PK(l0, h0), od, 0, 0, 0);
;     od = __builtin_amdgcn_mfma_f32_32x32x16_bf16(pa1, PK(l1, h1), od, 0, 0, 0);
;     od = __builtin_amdgcn_mfma_f32_32x32x16_bf16(pa2, PK(l2, h2), od, 0, 0, 0);
;     od = __builtin_amdgcn_mfma_f32_32x32x16_bf16(pa3, PK(l3, h3), od, 0, 0, 0);
;     ...
; }
; __device__ __forceinline__ void pv_d0(f32x16* o, int vb, bf16x8 pa0, bf16x8 pa1, bf16x8 pa2, bf16x8 pa3) {
;     pv_one<0>(o[0], vb, pa0, pa1, pa2, pa3); pv_one<1>(o[1], vb, pa0, pa1, pa2, pa3); pv_one<2>(o[2], vb, pa0, pa1, pa2, pa3); pv_one<3>(o[3], vb, pa0, pa1, pa2, pa3);
; }
.Lat_qkd_l:
	s_waitcnt lgkmcnt(0)
	v_mfma_f32_32x32x16_bf16 v[50:65], v[146:149], v[162:165], v[50:65]
	ds_read_b64_tr_b16 v[162:163], v244 offset:0x200
	ds_read_b64_tr_b16 v[164:165], v244 offset:0xa00
	v_mfma_f32_32x32x16_bf16 v[50:65], v[150:153], v[166:169], v[50:65]
	ds_read_b64_tr_b16 v[166:167], v244 offset:0x1200
	ds_read_b64_tr_b16 v[168:169], v244 offset:0x1a00
	v_mfma_f32_32x32x16_bf16 v[50:65], v[154:157], v[170:173], v[50:65]
	ds_read_b64_tr_b16 v[170:171], v244 offset:0x2200
	ds_read_b64_tr_b16 v[172:173], v244 offset:0x2a00
	v_mfma_f32_32x32x16_bf16 v[50:65], v[158:161], v[174:177], v[50:65]
	ds_read_b64_tr_b16 v[174:175], v244 offset:0x3200
	ds_read_b64_tr_b16 v[176:177], v244 offset:0x3a00
	s_waitcnt lgkmcnt(0)
	v_mfma_f32_32x32x16_bf16 v[34:49], v[146:149], v[162:165], v[34:49]
	ds_read_b64_tr_b16 v[162:163], v244 offset:0x400
	ds_read_b64_tr_b16 v[164:165], v244 offset:0xc00
	v_mfma_f32_32x32x16_bf16 v[34:49], v[150:153], v[166:169], v[34:49]
	ds_read_b64_tr_b16 v[166:167], v244 offset:0x1400
	ds_read_b64_tr_b16 v[168:169], v244 offset:0x1c00
	v_mfma_f32_32x32x16_bf16 v[34:49], v[154:157], v[170:173], v[34:49]
	ds_read_b64_tr_b16 v[170:171], v244 offset:0x2400
	ds_read_b64_tr_b16 v[172:173], v244 offset:0x2c00
	v_mfma_f32_32x32x16_bf16 v[34:49], v[158:161], v[174:177], v[34:49]
	ds_read_b64_tr_b16 v[174:175], v244 offset:0x3400
	ds_read_b64_tr_b16 v[176:177], v244 offset:0x3c00
	s_waitcnt lgkmcnt(0)
	v_mfma_f32_32x32x16_bf16 v[18:33], v[146:149], v[162:165], v[18:33]
	ds_read_b64_tr_b16 v[162:163], v244 offset:0x600
	ds_read_b64_tr_b16 v[164:165], v244 offset:0xe00
	v_mfma_f32_32x32x16_bf16 v[18:33], v[150:153], v[166:169], v[18:33]
	ds_read_b64_tr_b16 v[166:167], v244 offset:0x1600
	ds_read_b64_tr_b16 v[168:169], v244 offset:0x1e00
	v_mfma_f32_32x32x16_bf16 v[18:33], v[154:157], v[170:173], v[18:33]
	ds_read_b64_tr_b16 v[170:171], v244 offset:0x2600
	ds_read_b64_tr_b16 v[172:173], v244 offset:0x2e00
	v_mfma_f32_32x32x16_bf16 v[18:33], v[158:161], v[174:177], v[18:33]
	ds_read_b64_tr_b16 v[174:175], v244 offset:0x3600
	ds_read_b64_tr_b16 v[176:177], v244 offset:0x3e00
	s_waitcnt lgkmcnt(0)
	v_mfma_f32_32x32x16_bf16 v[2:17], v[146:149], v[162:165], v[2:17]
	v_mfma_f32_32x32x16_bf16 v[2:17], v[150:153], v[166:169], v[2:17]
	v_mfma_f32_32x32x16_bf16 v[2:17], v[154:157], v[170:173], v[2:17]
	v_mfma_f32_32x32x16_bf16 v[2:17], v[158:161], v[174:177], v[2:17]
	s_setprio 0
	s_cmp_gt_u32 s40, 61
	s_cbranch_scc1 .Lat_w0_l
	s_waitcnt vmcnt(3)
	s_branch .Lat_wd_l

; __device__ __forceinline__ void partialSM(f32x16& p0, f32x16& p1, float& m_reg, float& mn, float& alpha, float boff) {
;     ...
;     const float mnC = (boff - mn) * C;
; #pragma unroll
;     for (int r = 0; r < 16; ++r) p0[r] = fmaf(p0[r], C, mnC);
; #pragma unroll
;     for (int r = 0; r < 16; ++r) p1[r] = fmaf(p1[r], C, mnC);
; #pragma unroll
;     for (int r = 0; r < 16; ++r) p0[r] = __builtin_amdgcn_exp2f(p0[r]);
; }
; __device__ __forceinline__ void finishSM(f32x16& p0, f32x16& p1, float alpha, float& l_reg, bf16x8& pa0, bf16x8& pa1, bf16x8& pa2, bf16x8& pa3) {
; #pragma unroll
;     for (int r = 0; r < 16; ++r) p1[r] = __builtin_amdgcn_exp2f(p1[r]);
;     float ps = 0;
; #pragma unroll
;     for (int r = 0; r < 16; ++r) ps += p0[r];
; #pragma unroll
;     for (int r = 0; r < 16; ++r) ps += p1[r];
;     { auto rr = __builtin_amdgcn_permlane32_swap(__float_as_uint(ps), __float_as_uint(ps), false, false);
;       ps = __uint_as_float(rr[0]) + __uint_as_float(rr[1]); }
;     l_reg = l_reg * alpha + ps;
;     ...
;     PK4(p0, 0, pa0); PK4(p0, 8, pa1); PK4(p1, 0, pa2); PK4(p1, 8, pa3);
.Lat_noresc_l:
	v_cndmask_b32_e64 v243, v249, v243, s[0:1]
	v_sub_f32_e32 v0, v0, v243
	v_mul_f32_e32 v0, 0x3e38aa3b, v0
	v_fmamk_f32 v82, v82, 0x3e38aa3b, v0
	v_fmamk_f32 v83, v83, 0x3e38aa3b, v0
	v_fmamk_f32 v84, v84, 0x3e38aa3b, v0
	v_fmamk_f32 v85, v85, 0x3e38aa3b, v0
	v_fmamk_f32 v86, v86, 0x3e38aa3b, v0
	v_fmamk_f32 v87, v87, 0x3e38aa3b, v0
	v_fmamk_f32 v88, v88, 0x3e38aa3b, v0
	v_fmamk_f32 v89, v89, 0x3e38aa3b, v0
	v_fmamk_f32 v90, v90, 0x3e38aa3b, v0
	v_fmamk_f32 v91, v91, 0x3e38aa3b, v0
	v_fmamk_f32 v92, v92, 0x3e38aa3b, v0
	v_fmamk_f32 v93, v93, 0x3e38aa3b, v0
	v_fmamk_f32 v94, v94, 0x3e38aa3b, v0
	v_fmamk_f32 v95, v95, 0x3e38aa3b, v0
	v_fmamk_f32 v96, v96, 0x3e38aa3b, v0
	v_fmamk_f32 v97, v97, 0x3e38aa3b, v0
	v_fmamk_f32 v66, v66, 0x3e38aa3b, v0
	v_fmamk_f32 v67, v67, 0x3e38aa3b, v0
	v_fmamk_f32 v68, v68, 0x3e38aa3b, v0
	v_fmamk_f32 v69, v69, 0x3e38aa3b, v0
	v_fmamk_f32 v70, v70, 0x3e38aa3b, v0
	v_fmamk_f32 v71, v71, 0x3e38aa3b, v0
	v_fmamk_f32 v72, v72, 0x3e38aa3b, v0
	v_fmamk_f32 v73, v73, 0x3e38aa3b, v0
	v_fmamk_f32 v74, v74, 0x3e38aa3b, v0
	v_fmamk_f32 v75, v75, 0x3e38aa3b, v0
	v_fmamk_f32 v76, v76, 0x3e38aa3b, v0
	v_fmamk_f32 v77, v77, 0x3e38aa3b, v0
	v_fmamk_f32 v78, v78, 0x3e38aa3b, v0
	v_fmamk_f32 v79, v79, 0x3e38aa3b, v0
	v_fmamk_f32 v80, v80, 0x3e38aa3b, v0
	v_fmamk_f32 v81, v81, 0x3e38aa3b, v0
	v_exp_f32_e32 v82, v82
	v_exp_f32_e32 v83, v83
	v_exp_f32_e32 v84, v84
	v_exp_f32_e32 v85, v85
	v_exp_f32_e32 v86, v86
	v_exp_f32_e32 v87, v87
	v_exp_f32_e32 v88, v88
	v_exp_f32_e32 v89, v89
	v_exp_f32_e32 v90, v90
	v_exp_f32_e32 v91, v91
	v_exp_f32_e32 v92, v92
	v_exp_f32_e32 v93, v93
	v_exp_f32_e32 v94, v94
	v_exp_f32_e32 v95, v95
	v_exp_f32_e32 v96, v96
	v_exp_f32_e32 v97, v97
	v_exp_f32_e32 v66, v66
	v_add_f32_e32 v244, v82, v83
	v_exp_f32_e32 v67, v67
	v_add_f32_e32 v244, v84, v244
	v_exp_f32_e32 v68, v68
	v_add_f32_e32 v244, v85, v244
	v_exp_f32_e32 v69, v69
	v_add_f32_e32 v244, v86, v244
	v_exp_f32_e32 v70, v70
	v_add_f32_e32 v244, v87, v244
	v_exp_f32_e32 v71, v71
	v_add_f32_e32 v244, v88, v244
	v_exp_f32_e32 v72, v72
	v_add_f32_e32 v244, v89, v244
	v_exp_f32_e32 v73, v73
	v_add_f32_e32 v244, v90, v244
	v_exp_f32_e32 v74, v74
	v_add_f32_e32 v244, v91, v244
	v_exp_f32_e32 v75, v75
	v_add_f32_e32 v244, v92, v244
	v_exp_f32_e32 v76, v76
	v_add_f32_e32 v244, v93, v244
	v_exp_f32_e32 v77, v77
	v_add_f32_e32 v244, v94, v244
	v_exp_f32_e32 v78, v78
	v_add_f32_e32 v244, v95, v244
	v_exp_f32_e32 v79, v79
	v_add_f32_e32 v244, v96, v244
	v_exp_f32_e32 v80, v80
	v_add_f32_e32 v244, v97, v244
	v_exp_f32_e32 v81, v81
	v_add_f32_e32 v249, v66, v67
	v_add_f32_e32 v249, v68, v249
	v_add_f32_e32 v249, v69, v249
	v_add_f32_e32 v249, v70, v249
	v_add_f32_e32 v249, v71, v249
	v_add_f32_e32 v249, v72, v249
	v_add_f32_e32 v249, v73, v249
	v_add_f32_e32 v249, v74, v249
	v_add_f32_e32 v249, v75, v249
	v_add_f32_e32 v249, v76, v249
	v_add_f32_e32 v249, v77, v249
	v_add_f32_e32 v249, v78, v249
	v_add_f32_e32 v249, v79, v249
	v_add_f32_e32 v249, v80, v249
	v_add_f32_e32 v249, v81, v249
	v_add_f32_e32 v244, v244, v249
	v_fma_f32 v238, v238, v248, v244
	v_cvt_pk_bf16_f32 v146, v82, v83
	v_cvt_pk_bf16_f32 v147, v84, v85
	v_cvt_pk_bf16_f32 v148, v86, v87
	v_cvt_pk_bf16_f32 v149, v88, v89
	v_cvt_pk_bf16_f32 v150, v90, v91
	v_cvt_pk_bf16_f32 v151, v92, v93
	v_cvt_pk_bf16_f32 v152, v94, v95
	v_cvt_pk_bf16_f32 v153, v96, v97
	v_cvt_pk_bf16_f32 v154, v66, v67
	v_cvt_pk_bf16_f32 v155, v68, v69
	v_cvt_pk_bf16_f32 v156, v70, v71
	v_cvt_pk_bf16_f32 v157, v72, v73
	v_cvt_pk_bf16_f32 v158, v74, v75
	v_cvt_pk_bf16_f32 v159, v76, v77
	v_cvt_pk_bf16_f32 v160, v78, v79
	v_cvt_pk_bf16_f32 v161, v80, v81
	s_nop 1
	v_permlane32_swap_b32_e32 v146, v148
	v_permlane32_swap_b32_e32 v147, v149
	v_permlane32_swap_b32_e32 v150, v152
	v_permlane32_swap_b32_e32 v151, v153
	v_permlane32_swap_b32_e32 v154, v156
	v_permlane32_swap_b32_e32 v155, v157
	v_permlane32_swap_b32_e32 v158, v160
	v_permlane32_swap_b32_e32 v159, v161
	s_add_i32 s40, s40, 1
	s_addk_i32 s65, 0x40
	v_add_u32_e32 v245, 0x100, v245
	s_barrier
; #define SBAR() __builtin_amdgcn_sched_barrier(0)
; template <int D0> __device__ __forceinline__ void pv_one(f32x16& od, int vb, bf16x8 pa0, bf16x8 pa1, bf16x8 pa2, bf16x8 pa3) {
;     const s16x4 l0 = tr_read<v_rd_off(D0, 0, 0)>(vb), h0 = tr_read<v_rd_off(D0, 0, 1)>(vb), l1 = tr_read<v_rd_off(D0, 1, 0)>(vb), h1 = tr_read<v_rd_off(D0, 1, 1)>(vb);
;     const s16x4 l2 = tr_read<v_rd_off(D0, 2, 0)>(vb), h2 = tr_read<v_rd_off(D0, 2, 1)>(vb), l3 = tr_read<v_rd_off(D0, 3, 0)>(vb), h3 = tr_read<v_rd_off(D0, 3, 1)>(vb);
;     asm volatile("s_waitcnt lgkmcnt(0)" ::: "memory"); SBAR();
;     ...
;     od = __builtin_amdgcn_mfma_f32_32x32x16_bf16(pa0, PK(l0, h0), od, 0, 0, 0);
;     od = __builtin_amdgcn_mfma_f32_32x32x16_bf16(pa1, PK(l1, h1), od, 0, 0, 0);
;     od = __builtin_amdgcn_mfma_f32_32x32x16_bf16(pa2, PK(l2, h2), od, 0, 0, 0);
;     od = __builtin_amdgcn_mfma_f32_32x32x16_bf16(pa3, PK(l3, h3), od, 0, 0, 0);
;     ...
; }
; __device__ __forceinline__ void pv_d0(f32x16* o, int vb, bf16x8 pa0, bf16x8 pa1, bf16x8 pa2, bf16x8 pa3) {
;     pv_one<0>(o[0], vb, pa0, pa1, pa2, pa3); pv_one<1>(o[1], vb, pa0, pa1, pa2, pa3); pv_one<2>(o[2], vb, pa0, pa1, pa2, pa3); pv_one<3>(o[3], vb, pa0, pa1, pa2, pa3);
; }
; __device__ __forceinline__ void attn_unit(int b, int h, int qb, const bf16_t* __restrict__ proj, const float* __restrict__ btab, float lam, float outscale,
;                                           const float* __restrict__ gain, float* o1scr, bf16_t* merged, LAS char* lds) {
;     ...
;         finishSM(pB0, pB1, alB, l_reg, pa0, pa1, pa2, pa3); SBAR();
;         pv_d0(o, vb0 + bc * SHM_V, pa0, pa1, pa2, pa3);
	s_cmp_lt_u32 s40, 64
	s_cbranch_scc1 .Lat_loop
	s_setprio 1
	s_add_i32 s54, s40, 3
	s_and_b32 s54, s54, 3
	s_lshl_b32 s54, s54, 14
	v_add_u32_e32 v244, s54, v225
	ds_read_b64_tr_b16 v[162:163], v244 offset:0x0
	ds_read_b64_tr_b16 v[164:165], v244 offset:0x800
	ds_read_b64_tr_b16 v[166:167], v244 offset:0x1000
	ds_read_b64_tr_b16 v[168:169], v244 offset:0x1800
	ds_read_b64_tr_b16 v[170:171], v244 offset:0x2000
	ds_read_b64_tr_b16 v[172:173], v244 offset:0x2800
	ds_read_b64_tr_b16 v[174:175], v244 offset:0x3000
	ds_read_b64_tr_b16 v[176:177], v244 offset:0x3800
	s_waitcnt lgkmcnt(0)
	v_mfma_f32_32x32x16_bf16 v[50:65], v[146:149], v[162:165], v[50:65]
	ds_read_b64_tr_b16 v[162:163], v244 offset:0x200
	ds_read_b64_tr_b16 v[164:165], v244 offset:0xa00
	v_mfma_f32_32x32x16_bf16 v[50:65], v[150:153], v[166:169], v[50:65]
	ds_read_b64_tr_b16 v[166:167], v244 offset:0x1200
	ds_read_b64_tr_b16 v[168:169], v244 offset:0x1a00
	v_mfma_f32_32x32x16_bf16 v[50:65], v[154:157], v[170:173], v[50:65]
	ds_read_b64_tr_b16 v[170:171], v244 offset:0x2200
	ds_read_b64_tr_b16 v[172:173], v244 offset:0x2a00
	v_mfma_f32_32x32x16_bf16 v[50:65], v[158:161], v[174:177], v[50:65]
	ds_read_b64_tr_b16 v[174:175], v244 offset:0x3200
	ds_read_b64_tr_b16 v[176:177], v244 offset:0x3a00
	s_waitcnt lgkmcnt(0)
	v_mfma_f32_32x32x16_bf16 v[34:49], v[146:149], v[162:165], v[34:49]
	ds_read_b64_tr_b16 v[162:163], v244 offset:0x400
	ds_read_b64_tr_b16 v[164:165], v244 offset:0xc00
	v_mfma_f32_32x32x16_bf16 v[34:49], v[150:153], v[166:169], v[34:49]
	ds_read_b64_tr_b16 v[166:167], v244 offset:0x1400
	ds_read_b64_tr_b16 v[168:169], v244 offset:0x1c00
	v_mfma_f32_32x32x16_bf16 v[34:49], v[154:157], v[170:173], v[34:49]
	ds_read_b64_tr_b16 v[170:171], v244 offset:0x2400
	ds_read_b64_tr_b16 v[172:173], v244 offset:0x2c00
	v_mfma_f32_32x32x16_bf16 v[34:49], v[158:161], v[174:177], v[34:49]
	ds_read_b64_tr_b16 v[174:175], v244 offset:0x3400
	ds_read_b64_tr_b16 v[176:177], v244 offset:0x3c00
	s_waitcnt lgkmcnt(0)
	v_mfma_f32_32x32x16_bf16 v[18:33], v[146:149], v[162:165], v[18:33]
	ds_read_b64_tr_b16 v[162:163], v244 offset:0x600
	ds_read_b64_tr_b16 v[164:165], v244 offset:0xe00
	v_mfma_f32_32x32x16_bf16 v[18:33], v[150:153], v[166:169], v[18:33]
	ds_read_b64_tr_b16 v[166:167], v244 offset:0x1600
	ds_read_b64_tr_b16 v[168:169], v244 offset:0x1e00
	v_mfma_f32_32x32x16_bf16 v[18:33], v[154:157], v[170:173], v[18:33]
	ds_read_b64_tr_b16 v[170:171], v244 offset:0x2600
	ds_read_b64_tr_b16 v[172:173], v244 offset:0x2e00
	v_mfma_f32_32x32x16_bf16 v[18:33], v[158:161], v[174:177], v[18:33]
	ds_read_b64_tr_b16 v[174:175], v244 offset:0x3600
	ds_read_b64_tr_b16 v[176:177], v244 offset:0x3e00
	s_waitcnt lgkmcnt(0)
	v_mfma_f32_32x32x16_bf16 v[2:17], v[146:149], v[162:165], v[2:17]
	v_mfma_f32_32x32x16_bf16 v[2:17], v[150:153], v[166:169], v[2:17]
	v_mfma_f32_32x32x16_bf16 v[2:17], v[154:157], v[170:173], v[2:17]
	v_mfma_f32_32x32x16_bf16 v[2:17], v[158:161], v[174:177], v[2:17]
	s_setprio 0
	s_cmp_lg_u32 s67, 0
	s_cbranch_scc1 .Lat_fin
	s_barrier

; __device__ __forceinline__ void attn_unit(int b, int h, int qb, const bf16_t* __restrict__ proj, const float* __restrict__ btab, float lam, float outscale,
;                                           const float* __restrict__ gain, float* o1scr, bf16_t* merged, LAS char* lds) {
;     ...
;             for (int d0 = 0; d0 < 4; ++d0)
; #pragma unroll
;                 for (int r4 = 0; r4 < 4; ++r4) { const f32x4 p = o1p[d0 * 4 + r4];
; #pragma unroll
;                     for (int e = 0; e < 4; ++e) o[d0][4 * r4 + e] = p[e] - lam * (o[d0][4 * r4 + e] * rli[4 * r4 + e]); }
.LBB0_222:
	flat_load_dwordx4 v[66:69], v[74:75]
	flat_load_dwordx4 v[224:227], v[74:75] offset:16
	flat_load_dwordx4 v[228:231], v[74:75] offset:32
	flat_load_dwordx4 v[232:235], v[74:75] offset:48
	flat_load_dwordx4 v[236:239], v[74:75] offset:64
	flat_load_dwordx4 v[240:243], v[74:75] offset:80
	flat_load_dwordx4 v[244:247], v[74:75] offset:96
	flat_load_dwordx4 v[248:251], v[74:75] offset:112
	v_mul_f32_e32 v0, v50, v86
	v_xor_b32_e32 v152, 8, v208
	v_and_b32_e32 v171, 31, v88
	s_mov_b32 s0, 0x8000
	s_waitcnt vmcnt(0) lgkmcnt(0)
	v_fma_f32 v110, -v179, v0, v66
	v_mul_f32_e32 v0, v51, v87
	v_fma_f32 v107, -v179, v0, v67
	v_mul_f32_e32 v0, v52, v84
	v_fma_f32 v104, -v179, v0, v68
	v_mul_f32_e32 v0, v53, v85
	v_fma_f32 v101, -v179, v0, v69
	v_mov_b32_e32 v66, v224
	v_mov_b32_e32 v67, v225
	v_mov_b32_e32 v68, v226
	v_mov_b32_e32 v69, v227
	v_mul_f32_e32 v0, v54, v76
	v_fma_f32 v103, -v179, v0, v66
	v_mul_f32_e32 v0, v55, v77
	v_fma_f32 v100, -v179, v0, v67
	v_mul_f32_e32 v0, v56, v82
	v_fma_f32 v98, -v179, v0, v68
	v_mul_f32_e32 v0, v57, v83
	v_fma_f32 v96, -v179, v0, v69
	v_mov_b32_e32 v66, v228
	v_mov_b32_e32 v67, v229
	v_mov_b32_e32 v68, v230
	v_mov_b32_e32 v69, v231
	v_mul_f32_e32 v0, v58, v80
	v_fma_f32 v97, -v179, v0, v66
	v_mul_f32_e32 v0, v59, v81
	v_fma_f32 v95, -v179, v0, v67
	v_mul_f32_e32 v0, v60, v78
	v_fma_f32 v94, -v179, v0, v68
	v_mul_f32_e32 v0, v61, v79
	v_fma_f32 v92, -v179, v0, v69
	v_mov_b32_e32 v66, v232
	v_mov_b32_e32 v67, v233
	v_mov_b32_e32 v68, v234
	v_mov_b32_e32 v69, v235
	v_mul_f32_e32 v0, v62, v72
	v_fma_f32 v93, -v179, v0, v66
	v_mul_f32_e32 v0, v63, v73
	v_fma_f32 v91, -v179, v0, v67
	v_mul_f32_e32 v0, v64, v70
	v_fma_f32 v90, -v179, v0, v68
	v_mul_f32_e32 v0, v65, v71
	v_fma_f32 v89, -v179, v0, v69
	v_mov_b32_e32 v66, v236
	v_mov_b32_e32 v67, v237
	v_mov_b32_e32 v68, v238
	v_mov_b32_e32 v69, v239
	v_mul_f32_e32 v0, v34, v86
	v_fma_f32 v122, -v179, v0, v66
	v_mul_f32_e32 v0, v35, v87
	v_fma_f32 v120, -v179, v0, v67
	v_mul_f32_e32 v0, v36, v84
	v_fma_f32 v118, -v179, v0, v68
	v_mul_f32_e32 v0, v37, v85
	v_fma_f32 v116, -v179, v0, v69
	v_mov_b32_e32 v66, v240
	v_mov_b32_e32 v67, v241
	v_mov_b32_e32 v68, v242
	v_mov_b32_e32 v69, v243
	v_mul_f32_e32 v0, v38, v76
	v_fma_f32 v117, -v179, v0, v66
	v_mul_f32_e32 v0, v39, v77
	v_fma_f32 v115, -v179, v0, v67
	v_mul_f32_e32 v0, v40, v82
	v_fma_f32 v114, -v179, v0, v68
	v_mul_f32_e32 v0, v41, v83
	v_fma_f32 v112, -v179, v0, v69
	v_mov_b32_e32 v66, v244
	v_mov_b32_e32 v67, v245
	v_mov_b32_e32 v68, v246
	v_mov_b32_e32 v69, v247
	v_mul_f32_e32 v0, v42, v80
	v_fma_f32 v113, -v179, v0, v66
	v_mul_f32_e32 v0, v43, v81
	v_fma_f32 v111, -v179, v0, v67
	v_mul_f32_e32 v0, v44, v78
	v_fma_f32 v109, -v179, v0, v68
	v_mul_f32_e32 v0, v45, v79
	v_fma_f32 v106, -v179, v0, v69
	v_mov_b32_e32 v66, v248
	v_mov_b32_e32 v67, v249
	v_mov_b32_e32 v68, v250
	v_mov_b32_e32 v69, v251
	v_mul_f32_e32 v0, v46, v72
	v_fma_f32 v108, -v179, v0, v66
	v_mul_f32_e32 v0, v47, v73
	v_fma_f32 v105, -v179, v0, v67
	v_mul_f32_e32 v0, v48, v70
	v_fma_f32 v102, -v179, v0, v68
	v_mul_f32_e32 v0, v49, v71
	v_fma_f32 v99, -v179, v0, v69
	flat_load_dwordx4 v[66:69], v[74:75] offset:128
	flat_load_dwordx4 v[224:227], v[74:75] offset:144
	flat_load_dwordx4 v[228:231], v[74:75] offset:160
	flat_load_dwordx4 v[232:235], v[74:75] offset:176
	flat_load_dwordx4 v[236:239], v[74:75] offset:192
	flat_load_dwordx4 v[240:243], v[74:75] offset:208
	flat_load_dwordx4 v[244:247], v[74:75] offset:224
	flat_load_dwordx4 v[248:251], v[74:75] offset:240
	v_mul_f32_e32 v0, v18, v86
	s_waitcnt vmcnt(0) lgkmcnt(0)
	v_fma_f32 v136, -v179, v0, v66
	v_mul_f32_e32 v0, v19, v87
	v_fma_f32 v135, -v179, v0, v67
	v_mul_f32_e32 v0, v20, v84
	v_fma_f32 v134, -v179, v0, v68
	v_mul_f32_e32 v0, v21, v85
	v_fma_f32 v132, -v179, v0, v69
	v_mov_b32_e32 v66, v224
	v_mov_b32_e32 v67, v225
	v_mov_b32_e32 v68, v226
	v_mov_b32_e32 v69, v227
	v_mul_f32_e32 v0, v22, v76
	v_fma_f32 v133, -v179, v0, v66
	v_mul_f32_e32 v0, v23, v77
	v_fma_f32 v131, -v179, v0, v67
	v_mul_f32_e32 v0, v24, v82
	v_fma_f32 v129, -v179, v0, v68
	v_mul_f32_e32 v0, v25, v83
	v_fma_f32 v126, -v179, v0, v69
	v_mov_b32_e32 v66, v228
	v_mov_b32_e32 v67, v229
	v_mov_b32_e32 v68, v230
	v_mov_b32_e32 v69, v231
	v_mul_f32_e32 v0, v26, v80
	v_fma_f32 v130, -v179, v0, v66
	v_mul_f32_e32 v0, v27, v81
	v_fma_f32 v128, -v179, v0, v67
	v_mul_f32_e32 v0, v28, v78
	v_fma_f32 v125, -v179, v0, v68
	v_mul_f32_e32 v0, v29, v79
	v_fma_f32 v123, -v179, v0, v69
	v_mov_b32_e32 v66, v232
	v_mov_b32_e32 v67, v233
	v_mov_b32_e32 v68, v234
	v_mov_b32_e32 v69, v235
	v_mul_f32_e32 v0, v30, v72
	v_fma_f32 v127, -v179, v0, v66
	v_mul_f32_e32 v0, v31, v73
	v_fma_f32 v124, -v179, v0, v67
	v_mul_f32_e32 v0, v32, v70
	v_fma_f32 v121, -v179, v0, v68
	v_mul_f32_e32 v0, v33, v71
	v_fma_f32 v119, -v179, v0, v69
	v_mov_b32_e32 v66, v236
	v_mov_b32_e32 v67, v237
	v_mov_b32_e32 v68, v238
	v_mov_b32_e32 v69, v239
	v_mul_f32_e32 v0, v2, v86
	v_fma_f32 v148, -v179, v0, v66
	v_mul_f32_e32 v0, v3, v87
	v_fma_f32 v147, -v179, v0, v67
	v_mul_f32_e32 v0, v4, v84
	v_fma_f32 v145, -v179, v0, v68
	v_mul_f32_e32 v0, v5, v85
	v_fma_f32 v142, -v179, v0, v69
	v_mov_b32_e32 v66, v240
	v_mov_b32_e32 v67, v241
	v_mov_b32_e32 v68, v242
	v_mov_b32_e32 v69, v243
	v_mul_f32_e32 v0, v6, v76
	v_fma_f32 v146, -v179, v0, v66
	v_mul_f32_e32 v0, v7, v77
	v_fma_f32 v144, -v179, v0, v67
	v_mul_f32_e32 v0, v8, v82
	v_fma_f32 v141, -v179, v0, v68
	v_mul_f32_e32 v0, v9, v83
	v_fma_f32 v139, -v179, v0, v69
	v_mov_b32_e32 v66, v244
	v_mov_b32_e32 v67, v245
	v_mov_b32_e32 v68, v246
	v_mov_b32_e32 v69, v247
	v_mul_f32_e32 v0, v10, v80
	v_fma_f32 v143, -v179, v0, v66
; __device__ __forceinline__ void attn_unit(int b, int h, int qb, const bf16_t* __restrict__ proj, const float* __restrict__ btab, float lam, float outscale,
;                                           const float* __restrict__ gain, float* o1scr, bf16_t* merged, LAS char* lds) {
;     ...
;             float ssq[16];
; #pragma unroll
;             for (int r = 0; r < 16; ++r) { float a2 = 0.f;
; #pragma unroll
;                 for (int d0 = 0; d0 < 4; ++d0) a2 += o[d0][r] * o[d0][r];
;                 a2 += __shfl_xor(a2, 1); a2 += __shfl_xor(a2, 2); a2 += __shfl_xor(a2, 4); a2 += __shfl_xor(a2, 8); a2 += __shfl_xor(a2, 16);
;                 ssq[r] = __builtin_amdgcn_rsqf(a2 * (1.0f / 128.0f) + EPS) * outscale; }
	v_mul_f32_e32 v0, v11, v81
	v_fma_f32 v140, -v179, v0, v67
	v_mul_f32_e32 v0, v12, v78
	v_fma_f32 v138, -v179, v0, v68
	v_mul_f32_e32 v0, v13, v79
	v_fma_f32 v137, -v179, v0, v69
	v_mov_b32_e32 v66, v248
	v_mov_b32_e32 v67, v249
	v_mov_b32_e32 v68, v250
	v_mov_b32_e32 v69, v251
	v_mul_f32_e32 v0, v14, v72
	v_fma_f32 v151, -v179, v0, v66
	v_mul_f32_e32 v0, v15, v73
	v_fma_f32 v150, -v179, v0, v67
	v_mul_f32_e32 v0, v16, v70
	v_fma_f32 v149, -v179, v0, v68
	v_mul_f32_e32 v0, v17, v71
	v_and_b32_e32 v66, 64, v208
	v_fma_f32 v68, -v179, v0, v69
	v_xor_b32_e32 v0, 1, v208
	v_add_u32_e32 v69, 64, v66
	v_cmp_lt_i32_e32 vcc, v0, v69
	v_xor_b32_e32 v66, 2, v208
	v_xor_b32_e32 v67, 4, v208
	v_cndmask_b32_e32 v0, v208, v0, vcc
	v_cmp_lt_i32_e32 vcc, v66, v69
	v_lshlrev_b32_e32 v0, 2, v0
	s_nop 0
	v_cndmask_b32_e32 v66, v208, v66, vcc
	v_cmp_lt_i32_e32 vcc, v67, v69
	v_lshlrev_b32_e32 v66, 2, v66
	s_nop 0
	v_cndmask_b32_e32 v67, v208, v67, vcc
	v_cmp_lt_i32_e32 vcc, v152, v69
	v_lshlrev_b32_e32 v67, 2, v67
	s_nop 0
	v_cndmask_b32_e32 v152, v208, v152, vcc
	v_lshlrev_b32_e32 v159, 2, v152
	v_xor_b32_e32 v152, 16, v208
	v_cmp_lt_i32_e32 vcc, v152, v69
	s_nop 1
	v_cndmask_b32_e32 v69, v208, v152, vcc
	v_lshlrev_b32_e32 v160, 2, v69
	v_mul_f32_e32 v69, v122, v122
	v_fmac_f32_e32 v69, v110, v110
	v_fmac_f32_e32 v69, v136, v136
	v_fmac_f32_e32 v69, v148, v148
	ds_bpermute_b32 v152, v0, v69
	s_waitcnt lgkmcnt(0)
	v_add_f32_e32 v69, v69, v152
	ds_bpermute_b32 v152, v66, v69
	s_waitcnt lgkmcnt(0)
	v_add_f32_e32 v69, v69, v152
	ds_bpermute_b32 v152, v67, v69
	s_waitcnt lgkmcnt(0)
	v_add_f32_e32 v69, v69, v152
	ds_bpermute_b32 v152, v159, v69
	s_waitcnt lgkmcnt(0)
	v_add_f32_e32 v69, v69, v152
	ds_bpermute_b32 v152, v160, v69
	s_waitcnt lgkmcnt(0)
	v_add_f32_e32 v69, v69, v152
	v_mul_f32_e32 v152, v120, v120
	v_fmac_f32_e32 v152, v107, v107
	v_fmac_f32_e32 v152, v135, v135
	v_fmac_f32_e32 v152, v147, v147
	ds_bpermute_b32 v153, v0, v152
	v_fmamk_f32 v69, v69, 0x3c000000, v207
	v_rsq_f32_e32 v69, v69
	s_waitcnt lgkmcnt(0)
	v_add_f32_e32 v152, v152, v153
	ds_bpermute_b32 v153, v66, v152
	v_mul_f32_e32 v69, v221, v69
	s_waitcnt lgkmcnt(0)
	v_add_f32_e32 v152, v152, v153
	ds_bpermute_b32 v153, v67, v152
	s_waitcnt lgkmcnt(0)
	v_add_f32_e32 v152, v152, v153
	ds_bpermute_b32 v153, v159, v152
	s_waitcnt lgkmcnt(0)
	v_add_f32_e32 v152, v152, v153
	ds_bpermute_b32 v153, v160, v152
	s_waitcnt lgkmcnt(0)
	v_add_f32_e32 v152, v152, v153
	v_mul_f32_e32 v153, v118, v118
	v_fmac_f32_e32 v153, v104, v104
	v_fmac_f32_e32 v153, v134, v134
	v_fmac_f32_e32 v153, v145, v145
	ds_bpermute_b32 v154, v0, v153
	v_fmamk_f32 v152, v152, 0x3c000000, v207
	v_rsq_f32_e32 v152, v152
	s_waitcnt lgkmcnt(0)
	v_add_f32_e32 v153, v153, v154
	ds_bpermute_b32 v154, v66, v153
	v_mul_f32_e32 v152, v221, v152
	s_waitcnt lgkmcnt(0)
	v_add_f32_e32 v153, v153, v154
	ds_bpermute_b32 v154, v67, v153
	s_waitcnt lgkmcnt(0)
	v_add_f32_e32 v153, v153, v154
	ds_bpermute_b32 v154, v159, v153
	s_waitcnt lgkmcnt(0)
	v_add_f32_e32 v153, v153, v154
	ds_bpermute_b32 v154, v160, v153
	s_waitcnt lgkmcnt(0)
	v_add_f32_e32 v153, v153, v154
	v_mul_f32_e32 v154, v116, v116
	v_fmac_f32_e32 v154, v101, v101
	v_fmac_f32_e32 v154, v132, v132
	v_fmac_f32_e32 v154, v142, v142
	ds_bpermute_b32 v155, v0, v154
	v_fmamk_f32 v153, v153, 0x3c000000, v207
	v_rsq_f32_e32 v153, v153
	s_waitcnt lgkmcnt(0)
	v_add_f32_e32 v154, v154, v155
	ds_bpermute_b32 v155, v66, v154
	v_mul_f32_e32 v153, v221, v153
	s_waitcnt lgkmcnt(0)
	v_add_f32_e32 v154, v154, v155
	ds_bpermute_b32 v155, v67, v154
	s_waitcnt lgkmcnt(0)
	v_add_f32_e32 v154, v154, v155
	ds_bpermute_b32 v155, v159, v154
	s_waitcnt lgkmcnt(0)
	v_add_f32_e32 v154, v154, v155
	ds_bpermute_b32 v155, v160, v154
	s_waitcnt lgkmcnt(0)
	v_add_f32_e32 v154, v154, v155
	v_mul_f32_e32 v155, v117, v117
	v_fmac_f32_e32 v155, v103, v103
	v_fmac_f32_e32 v155, v133, v133
	v_fmac_f32_e32 v155, v146, v146
	ds_bpermute_b32 v156, v0, v155
	v_fmamk_f32 v154, v154, 0x3c000000, v207
	v_rsq_f32_e32 v154, v154
	s_waitcnt lgkmcnt(0)
	v_add_f32_e32 v155, v155, v156
	ds_bpermute_b32 v156, v66, v155
	v_mul_f32_e32 v154, v221, v154
	s_waitcnt lgkmcnt(0)
	v_add_f32_e32 v155, v155, v156
	ds_bpermute_b32 v156, v67, v155
	s_waitcnt lgkmcnt(0)
	v_add_f32_e32 v155, v155, v156
	ds_bpermute_b32 v156, v159, v155
	s_waitcnt lgkmcnt(0)
	v_add_f32_e32 v155, v155, v156
	ds_bpermute_b32 v156, v160, v155
	s_waitcnt lgkmcnt(0)
	v_add_f32_e32 v155, v155, v156
	v_mul_f32_e32 v156, v115, v115
	v_fmac_f32_e32 v156, v100, v100
	v_fmac_f32_e32 v156, v131, v131
	v_fmac_f32_e32 v156, v144, v144
	ds_bpermute_b32 v157, v0, v156
	v_fmamk_f32 v155, v155, 0x3c000000, v207
	v_rsq_f32_e32 v155, v155
	s_waitcnt lgkmcnt(0)
	v_add_f32_e32 v156, v156, v157
	ds_bpermute_b32 v157, v66, v156
	v_mul_f32_e32 v155, v221, v155
	s_waitcnt lgkmcnt(0)
	v_add_f32_e32 v156, v156, v157
	ds_bpermute_b32 v157, v67, v156
	s_waitcnt lgkmcnt(0)
	v_add_f32_e32 v156, v156, v157
	ds_bpermute_b32 v157, v159, v156
	s_waitcnt lgkmcnt(0)
	v_add_f32_e32 v156, v156, v157
	ds_bpermute_b32 v157, v160, v156
	s_waitcnt lgkmcnt(0)
	v_add_f32_e32 v156, v156, v157
	v_mul_f32_e32 v157, v114, v114
	v_fmac_f32_e32 v157, v98, v98
	v_fmac_f32_e32 v157, v129, v129
	v_fmac_f32_e32 v157, v141, v141
	ds_bpermute_b32 v158, v0, v157
	v_fmamk_f32 v156, v156, 0x3c000000, v207
	v_rsq_f32_e32 v156, v156
	s_waitcnt lgkmcnt(0)
	v_add_f32_e32 v157, v157, v158
	ds_bpermute_b32 v158, v66, v157
	v_mul_f32_e32 v156, v221, v156
	s_waitcnt lgkmcnt(0)
	v_add_f32_e32 v157, v157, v158
	ds_bpermute_b32 v158, v67, v157
	s_waitcnt lgkmcnt(0)
	v_add_f32_e32 v157, v157, v158
	ds_bpermute_b32 v158, v159, v157
	s_waitcnt lgkmcnt(0)
; __device__ __forceinline__ void attn_unit(int b, int h, int qb, const bf16_t* __restrict__ proj, const float* __restrict__ btab, float lam, float outscale,
;                                           const float* __restrict__ gain, float* o1scr, bf16_t* merged, LAS char* lds) {
;     ...
;             float ssq[16];
; #pragma unroll
;             for (int r = 0; r < 16; ++r) { float a2 = 0.f;
; #pragma unroll
;                 for (int d0 = 0; d0 < 4; ++d0) a2 += o[d0][r] * o[d0][r];
;                 a2 += __shfl_xor(a2, 1); a2 += __shfl_xor(a2, 2); a2 += __shfl_xor(a2, 4); a2 += __shfl_xor(a2, 8); a2 += __shfl_xor(a2, 16);
;                 ssq[r] = __builtin_amdgcn_rsqf(a2 * (1.0f / 128.0f) + EPS) * outscale; }
	v_add_f32_e32 v157, v157, v158
	ds_bpermute_b32 v158, v160, v157
	s_waitcnt lgkmcnt(0)
	v_add_f32_e32 v157, v157, v158
	v_mul_f32_e32 v158, v112, v112
	v_fmac_f32_e32 v158, v96, v96
	v_fmac_f32_e32 v158, v126, v126
	v_fmac_f32_e32 v158, v139, v139
	ds_bpermute_b32 v161, v0, v158
	v_fmamk_f32 v157, v157, 0x3c000000, v207
	v_rsq_f32_e32 v157, v157
	s_waitcnt lgkmcnt(0)
	v_add_f32_e32 v158, v158, v161
	ds_bpermute_b32 v161, v66, v158
	v_mul_f32_e32 v157, v221, v157
	s_waitcnt lgkmcnt(0)
	v_add_f32_e32 v158, v158, v161
	ds_bpermute_b32 v161, v67, v158
	s_waitcnt lgkmcnt(0)
	v_add_f32_e32 v158, v158, v161
	ds_bpermute_b32 v161, v159, v158
	s_waitcnt lgkmcnt(0)
	v_add_f32_e32 v158, v158, v161
	ds_bpermute_b32 v161, v160, v158
	s_waitcnt lgkmcnt(0)
	v_add_f32_e32 v158, v158, v161
	v_mul_f32_e32 v161, v113, v113
	v_fmac_f32_e32 v161, v97, v97
	v_fmac_f32_e32 v161, v130, v130
	v_fmac_f32_e32 v161, v143, v143
	ds_bpermute_b32 v162, v0, v161
	v_fmamk_f32 v158, v158, 0x3c000000, v207
	v_rsq_f32_e32 v158, v158
	s_waitcnt lgkmcnt(0)
	v_add_f32_e32 v161, v161, v162
	ds_bpermute_b32 v162, v66, v161
	v_mul_f32_e32 v158, v221, v158
	s_waitcnt lgkmcnt(0)
	v_add_f32_e32 v161, v161, v162
	ds_bpermute_b32 v162, v67, v161
	s_waitcnt lgkmcnt(0)
	v_add_f32_e32 v161, v161, v162
	ds_bpermute_b32 v162, v159, v161
	s_waitcnt lgkmcnt(0)
	v_add_f32_e32 v161, v161, v162
	ds_bpermute_b32 v162, v160, v161
	s_waitcnt lgkmcnt(0)
	v_add_f32_e32 v161, v161, v162
	v_mul_f32_e32 v162, v111, v111
	v_fmac_f32_e32 v162, v95, v95
	v_fmac_f32_e32 v162, v128, v128
	v_fmac_f32_e32 v162, v140, v140
	ds_bpermute_b32 v163, v0, v162
	v_fmamk_f32 v161, v161, 0x3c000000, v207
	v_rsq_f32_e32 v161, v161
	s_waitcnt lgkmcnt(0)
	v_add_f32_e32 v162, v162, v163
	ds_bpermute_b32 v163, v66, v162
	v_mul_f32_e32 v161, v221, v161
	s_waitcnt lgkmcnt(0)
	v_add_f32_e32 v162, v162, v163
	ds_bpermute_b32 v163, v67, v162
	s_waitcnt lgkmcnt(0)
	v_add_f32_e32 v162, v162, v163
	ds_bpermute_b32 v163, v159, v162
	s_waitcnt lgkmcnt(0)
	v_add_f32_e32 v162, v162, v163
	ds_bpermute_b32 v163, v160, v162
	s_waitcnt lgkmcnt(0)
	v_add_f32_e32 v162, v162, v163
	v_mul_f32_e32 v163, v109, v109
	v_fmac_f32_e32 v163, v94, v94
	v_fmac_f32_e32 v163, v125, v125
	v_fmac_f32_e32 v163, v138, v138
	ds_bpermute_b32 v164, v0, v163
	v_fmamk_f32 v162, v162, 0x3c000000, v207
	v_rsq_f32_e32 v162, v162
	s_waitcnt lgkmcnt(0)
	v_add_f32_e32 v163, v163, v164
	ds_bpermute_b32 v164, v66, v163
	v_mul_f32_e32 v162, v221, v162
	s_waitcnt lgkmcnt(0)
	v_add_f32_e32 v163, v163, v164
	ds_bpermute_b32 v164, v67, v163
	s_waitcnt lgkmcnt(0)
	v_add_f32_e32 v163, v163, v164
	ds_bpermute_b32 v164, v159, v163
	s_waitcnt lgkmcnt(0)
	v_add_f32_e32 v163, v163, v164
	ds_bpermute_b32 v164, v160, v163
	s_waitcnt lgkmcnt(0)
	v_add_f32_e32 v163, v163, v164
	v_mul_f32_e32 v164, v106, v106
	v_fmac_f32_e32 v164, v92, v92
	v_fmac_f32_e32 v164, v123, v123
	v_fmac_f32_e32 v164, v137, v137
	ds_bpermute_b32 v165, v0, v164
	v_fmamk_f32 v163, v163, 0x3c000000, v207
	v_rsq_f32_e32 v163, v163
	s_waitcnt lgkmcnt(0)
	v_add_f32_e32 v164, v164, v165
	ds_bpermute_b32 v165, v66, v164
	v_mul_f32_e32 v163, v221, v163
	s_waitcnt lgkmcnt(0)
	v_add_f32_e32 v164, v164, v165
	ds_bpermute_b32 v165, v67, v164
	s_waitcnt lgkmcnt(0)
	v_add_f32_e32 v164, v164, v165
	ds_bpermute_b32 v165, v159, v164
	s_waitcnt lgkmcnt(0)
	v_add_f32_e32 v164, v164, v165
	ds_bpermute_b32 v165, v160, v164
	s_waitcnt lgkmcnt(0)
	v_add_f32_e32 v164, v164, v165
	v_mul_f32_e32 v165, v108, v108
	v_fmac_f32_e32 v165, v93, v93
	v_fmac_f32_e32 v165, v127, v127
	v_fmac_f32_e32 v165, v151, v151
	ds_bpermute_b32 v166, v0, v165
	v_fmamk_f32 v164, v164, 0x3c000000, v207
	v_rsq_f32_e32 v164, v164
	s_waitcnt lgkmcnt(0)
	v_add_f32_e32 v165, v165, v166
	ds_bpermute_b32 v166, v66, v165
	v_mul_f32_e32 v164, v221, v164
	s_waitcnt lgkmcnt(0)
	v_add_f32_e32 v165, v165, v166
	ds_bpermute_b32 v166, v67, v165
	s_waitcnt lgkmcnt(0)
	v_add_f32_e32 v165, v165, v166
	ds_bpermute_b32 v166, v159, v165
	s_waitcnt lgkmcnt(0)
	v_add_f32_e32 v165, v165, v166
	ds_bpermute_b32 v166, v160, v165
	s_waitcnt lgkmcnt(0)
	v_add_f32_e32 v165, v165, v166
	v_fmamk_f32 v165, v165, 0x3c000000, v207
	v_rsq_f32_e32 v165, v165
	s_nop 0
	v_mul_f32_e32 v167, v221, v165
	v_mul_f32_e32 v165, v105, v105
	v_fmac_f32_e32 v165, v91, v91
	v_fmac_f32_e32 v165, v124, v124
	v_fmac_f32_e32 v165, v150, v150
	ds_bpermute_b32 v166, v0, v165
	s_waitcnt lgkmcnt(0)
	v_add_f32_e32 v165, v165, v166
	ds_bpermute_b32 v166, v66, v165
	s_waitcnt lgkmcnt(0)
	v_add_f32_e32 v165, v165, v166
	ds_bpermute_b32 v166, v67, v165
	s_waitcnt lgkmcnt(0)
	v_add_f32_e32 v165, v165, v166
	ds_bpermute_b32 v166, v159, v165
	s_waitcnt lgkmcnt(0)
	v_add_f32_e32 v165, v165, v166
	ds_bpermute_b32 v166, v160, v165
	s_waitcnt lgkmcnt(0)
	v_add_f32_e32 v165, v165, v166
	v_fmamk_f32 v165, v165, 0x3c000000, v207
	v_rsq_f32_e32 v165, v165
	s_nop 0
	v_mul_f32_e32 v166, v221, v165
	v_mul_f32_e32 v165, v102, v102
	v_fmac_f32_e32 v165, v90, v90
	v_fmac_f32_e32 v165, v121, v121
	v_fmac_f32_e32 v165, v149, v149
	ds_bpermute_b32 v168, v0, v165
	s_waitcnt lgkmcnt(0)
	v_add_f32_e32 v165, v165, v168
	ds_bpermute_b32 v168, v66, v165
	s_waitcnt lgkmcnt(0)
	v_add_f32_e32 v165, v165, v168
	ds_bpermute_b32 v168, v67, v165
	s_waitcnt lgkmcnt(0)
	v_add_f32_e32 v165, v165, v168
	ds_bpermute_b32 v168, v159, v165
	s_waitcnt lgkmcnt(0)
	v_add_f32_e32 v165, v165, v168
	ds_bpermute_b32 v168, v160, v165
	s_waitcnt lgkmcnt(0)
	v_add_f32_e32 v165, v165, v168
	v_mul_f32_e32 v168, v99, v99
	v_fmac_f32_e32 v168, v89, v89
	v_fmac_f32_e32 v168, v119, v119
	v_fmac_f32_e32 v168, v68, v68
	ds_bpermute_b32 v0, v0, v168
	v_fmamk_f32 v165, v165, 0x3c000000, v207
	v_rsq_f32_e32 v165, v165
	s_waitcnt lgkmcnt(0)
; __device__ __forceinline__ unsigned f2bf(float f) { unsigned u = __builtin_bit_cast(unsigned, f); return (u + 0x7fffu + ((u >> 16) & 1u)) >> 16; }
; __device__ __forceinline__ void attn_unit(int b, int h, int qb, const bf16_t* __restrict__ proj, const float* __restrict__ btab, float lam, float outscale,
;                                           const float* __restrict__ gain, float* o1scr, bf16_t* merged, LAS char* lds) {
;     ...
;             const int r32l = tl & 31, hil = (tl >> 5) & 1;
;             float gn[4];
; #pragma unroll
;             for (int d0 = 0; d0 < 4; ++d0) gn[d0] = gain[h * 128 + d0 * 32 + r32l];
;             bf16_t* Ow = merged + (rowbase + qw + 4 * hil) * D + h * 128 + r32l;
; #pragma unroll
;             for (int r = 0; r < 16; ++r) { bf16_t* orp = Ow + (long)((r & 3) + 8 * (r >> 2)) * D;
; #pragma unroll
;                 for (int d0 = 0; d0 < 4; ++d0) orp[d0 * 32] = (bf16_t)f2bf(o[d0][r] * ssq[r] * gn[d0]); }
	v_add_f32_e32 v0, v168, v0
	ds_bpermute_b32 v66, v66, v0
	v_mul_f32_e32 v165, v221, v165
	s_waitcnt lgkmcnt(0)
	v_add_f32_e32 v0, v0, v66
	ds_bpermute_b32 v66, v67, v0
	s_waitcnt lgkmcnt(0)
	v_add_f32_e32 v0, v0, v66
	ds_bpermute_b32 v66, v159, v0
	s_waitcnt lgkmcnt(0)
	v_add_f32_e32 v0, v0, v66
	ds_bpermute_b32 v66, v160, v0
	s_waitcnt lgkmcnt(0)
	v_add_f32_e32 v0, v0, v66
	v_fmamk_f32 v0, v0, 0x3c000000, v207
	v_rsq_f32_e32 v0, v0
	s_nop 0
	v_mul_f32_e32 v159, v221, v0
	v_or_b32_e32 v0, s48, v171
	v_lshlrev_b32_e32 v0, 2, v0
	v_lshl_add_u64 v[66:67], s[42:43], 0, v[0:1]
	flat_load_dword v160, v[66:67]
	flat_load_dword v168, v[66:67] offset:128
	flat_load_dword v169, v[66:67] offset:256
	flat_load_dword v170, v[66:67] offset:384
	v_lshrrev_b32_e32 v0, 3, v88
	v_and_or_b32 v66, v0, 4, s49
	v_mov_b32_e32 v67, s50
	v_lshlrev_b64 v[66:67], 12, v[66:67]
	v_lshl_add_u64 v[66:67], s[8:9], 0, v[66:67]
	v_lshlrev_b32_e32 v0, 1, v171
	v_lshl_add_u64 v[66:67], v[66:67], 0, v[0:1]
	v_mul_f32_e32 v0, v110, v69
	v_add_co_u32_e32 v172, vcc, s94, v66
	s_waitcnt vmcnt(0) lgkmcnt(0)
	v_mul_f32_e32 v0, v0, v160
	v_bfe_u32 v88, v0, 16, 1
	v_add3_u32 v0, v0, v88, s91
	flat_store_short_d16_hi v[66:67], v0
	v_mul_f32_e32 v0, v122, v69
	v_mul_f32_e32 v0, v0, v168
	v_bfe_u32 v88, v0, 16, 1
	v_add3_u32 v0, v0, v88, s91
	flat_store_short_d16_hi v[66:67], v0 offset:64
	v_mul_f32_e32 v0, v136, v69
	v_mul_f32_e32 v0, v0, v169
	v_bfe_u32 v88, v0, 16, 1
	v_add3_u32 v0, v0, v88, s91
	flat_store_short_d16_hi v[66:67], v0 offset:128
	v_mul_f32_e32 v0, v148, v69
	v_mul_f32_e32 v0, v0, v170
	v_bfe_u32 v69, v0, 16, 1
	v_add3_u32 v0, v0, v69, s91
	flat_store_short_d16_hi v[66:67], v0 offset:192
	v_mul_f32_e32 v0, v107, v152
	v_mul_f32_e32 v0, v0, v160
	v_bfe_u32 v69, v0, 16, 1
	v_add3_u32 v0, v0, v69, s91
	v_addc_co_u32_e32 v173, vcc, 0, v67, vcc
	flat_store_short_d16_hi v[172:173], v0
	v_mul_f32_e32 v0, v120, v152
	v_mul_f32_e32 v0, v0, v168
	v_bfe_u32 v69, v0, 16, 1
	v_add3_u32 v0, v0, v69, s91
	flat_store_short_d16_hi v[172:173], v0 offset:64
	v_mul_f32_e32 v0, v135, v152
	v_mul_f32_e32 v0, v0, v169
	v_bfe_u32 v69, v0, 16, 1
	v_add3_u32 v0, v0, v69, s91
	flat_store_short_d16_hi v[172:173], v0 offset:128
	v_mul_f32_e32 v0, v147, v152
	v_mul_f32_e32 v0, v0, v170
	v_bfe_u32 v69, v0, 16, 1
	v_add3_u32 v0, v0, v69, s91
	flat_store_short_d16_hi v[172:173], v0 offset:192
	v_mul_f32_e32 v0, v104, v153
	v_mul_f32_e32 v0, v0, v160
	v_bfe_u32 v69, v0, 16, 1
	v_add_co_u32_e32 v172, vcc, s17, v66
	v_add3_u32 v0, v0, v69, s91
	s_nop 0
	v_addc_co_u32_e32 v173, vcc, 0, v67, vcc
	flat_store_short_d16_hi v[172:173], v0
	v_mul_f32_e32 v0, v118, v153
	v_mul_f32_e32 v0, v0, v168
	v_bfe_u32 v69, v0, 16, 1
	v_add3_u32 v0, v0, v69, s91
	flat_store_short_d16_hi v[172:173], v0 offset:64
	v_mul_f32_e32 v0, v134, v153
	v_mul_f32_e32 v0, v0, v169
	v_bfe_u32 v69, v0, 16, 1
	v_add3_u32 v0, v0, v69, s91
	flat_store_short_d16_hi v[172:173], v0 offset:128
	v_mul_f32_e32 v0, v145, v153
	v_mul_f32_e32 v0, v0, v170
	v_bfe_u32 v69, v0, 16, 1
	v_add3_u32 v0, v0, v69, s91
	flat_store_short_d16_hi v[172:173], v0 offset:192
	v_mul_f32_e32 v0, v101, v154
	v_mul_f32_e32 v0, v0, v160
	v_bfe_u32 v69, v0, 16, 1
	v_add_co_u32_e32 v134, vcc, s59, v66
	v_add3_u32 v0, v0, v69, s91
	s_nop 0
	v_addc_co_u32_e32 v135, vcc, 0, v67, vcc
	flat_store_short_d16_hi v[134:135], v0
	v_mul_f32_e32 v0, v116, v154
	v_mul_f32_e32 v0, v0, v168
	v_bfe_u32 v69, v0, 16, 1
	v_add3_u32 v0, v0, v69, s91
	flat_store_short_d16_hi v[134:135], v0 offset:64
	v_mul_f32_e32 v0, v132, v154
	v_mul_f32_e32 v0, v0, v169
	v_bfe_u32 v69, v0, 16, 1
	v_add3_u32 v0, v0, v69, s91
	flat_store_short_d16_hi v[134:135], v0 offset:128
	v_mul_f32_e32 v0, v142, v154
	v_mul_f32_e32 v0, v0, v170
	v_bfe_u32 v69, v0, 16, 1
	v_add3_u32 v0, v0, v69, s91
	flat_store_short_d16_hi v[134:135], v0 offset:192
	v_mul_f32_e32 v0, v103, v155
	v_mul_f32_e32 v0, v0, v160
	v_bfe_u32 v69, v0, 16, 1
	v_add_co_u32_e32 v134, vcc, s0, v66
	v_add3_u32 v0, v0, v69, s91
	s_nop 0
	v_addc_co_u32_e32 v135, vcc, 0, v67, vcc
	flat_store_short_d16_hi v[134:135], v0
	v_mul_f32_e32 v0, v117, v155
	v_mul_f32_e32 v0, v0, v168
	v_bfe_u32 v69, v0, 16, 1
	v_add3_u32 v0, v0, v69, s91
	flat_store_short_d16_hi v[134:135], v0 offset:64
	v_mul_f32_e32 v0, v133, v155
	v_mul_f32_e32 v0, v0, v169
	v_bfe_u32 v69, v0, 16, 1
	v_add3_u32 v0, v0, v69, s91
	flat_store_short_d16_hi v[134:135], v0 offset:128
	v_mul_f32_e32 v0, v146, v155
	v_mul_f32_e32 v0, v0, v170
	v_bfe_u32 v69, v0, 16, 1
	v_add3_u32 v0, v0, v69, s91
	flat_store_short_d16_hi v[134:135], v0 offset:192
	v_mul_f32_e32 v0, v100, v156
	v_mul_f32_e32 v0, v0, v160
	s_mov_b32 s0, 0x9000
	v_bfe_u32 v69, v0, 16, 1
	v_add_co_u32_e32 v100, vcc, s0, v66
	v_add3_u32 v0, v0, v69, s91
	s_nop 0
	v_addc_co_u32_e32 v101, vcc, 0, v67, vcc
	flat_store_short_d16_hi v[100:101], v0
	v_mul_f32_e32 v0, v115, v156
	v_mul_f32_e32 v0, v0, v168
	v_bfe_u32 v69, v0, 16, 1
	v_add3_u32 v0, v0, v69, s91
	flat_store_short_d16_hi v[100:101], v0 offset:64
	v_mul_f32_e32 v0, v131, v156
	v_mul_f32_e32 v0, v0, v169
	v_bfe_u32 v69, v0, 16, 1
	v_add3_u32 v0, v0, v69, s91
	flat_store_short_d16_hi v[100:101], v0 offset:128
	v_mul_f32_e32 v0, v144, v156
	v_mul_f32_e32 v0, v0, v170
	v_bfe_u32 v69, v0, 16, 1
	v_add3_u32 v0, v0, v69, s91
	flat_store_short_d16_hi v[100:101], v0 offset:192
	v_mul_f32_e32 v0, v98, v157
	v_mul_f32_e32 v0, v0, v160
	s_mov_b32 s0, 0xa000
	v_bfe_u32 v69, v0, 16, 1
	v_add_co_u32_e32 v100, vcc, s0, v66
	v_add3_u32 v0, v0, v69, s91
	s_nop 0
	v_addc_co_u32_e32 v101, vcc, 0, v67, vcc
	flat_store_short_d16_hi v[100:101], v0
	v_mul_f32_e32 v0, v114, v157
	v_mul_f32_e32 v0, v0, v168
; __device__ __forceinline__ unsigned f2bf(float f) { unsigned u = __builtin_bit_cast(unsigned, f); return (u + 0x7fffu + ((u >> 16) & 1u)) >> 16; }
; __device__ __forceinline__ void attn_unit(int b, int h, int qb, const bf16_t* __restrict__ proj, const float* __restrict__ btab, float lam, float outscale,
;                                           const float* __restrict__ gain, float* o1scr, bf16_t* merged, LAS char* lds) {
;     ...
;             bf16_t* Ow = merged + (rowbase + qw + 4 * hil) * D + h * 128 + r32l;
; #pragma unroll
;             for (int r = 0; r < 16; ++r) { bf16_t* orp = Ow + (long)((r & 3) + 8 * (r >> 2)) * D;
; #pragma unroll
;                 for (int d0 = 0; d0 < 4; ++d0) orp[d0 * 32] = (bf16_t)f2bf(o[d0][r] * ssq[r] * gn[d0]); }
	v_bfe_u32 v69, v0, 16, 1
	v_add3_u32 v0, v0, v69, s91
	flat_store_short_d16_hi v[100:101], v0 offset:64
	v_mul_f32_e32 v0, v129, v157
	v_mul_f32_e32 v0, v0, v169
	v_bfe_u32 v69, v0, 16, 1
	v_add3_u32 v0, v0, v69, s91
	flat_store_short_d16_hi v[100:101], v0 offset:128
	v_mul_f32_e32 v0, v141, v157
	v_mul_f32_e32 v0, v0, v170
	v_bfe_u32 v69, v0, 16, 1
	v_add3_u32 v0, v0, v69, s91
	flat_store_short_d16_hi v[100:101], v0 offset:192
	v_mul_f32_e32 v0, v96, v158
	v_mul_f32_e32 v0, v0, v160
	v_bfe_u32 v69, v0, 16, 1
	v_add_co_u32_e32 v100, vcc, s55, v66
	v_add3_u32 v0, v0, v69, s91
	s_nop 0
	v_addc_co_u32_e32 v101, vcc, 0, v67, vcc
	flat_store_short_d16_hi v[100:101], v0
	v_mul_f32_e32 v0, v112, v158
	v_mul_f32_e32 v0, v0, v168
	v_bfe_u32 v69, v0, 16, 1
	v_add3_u32 v0, v0, v69, s91
	flat_store_short_d16_hi v[100:101], v0 offset:64
	v_mul_f32_e32 v0, v126, v158
	v_mul_f32_e32 v0, v0, v169
	v_bfe_u32 v69, v0, 16, 1
	v_add3_u32 v0, v0, v69, s91
	flat_store_short_d16_hi v[100:101], v0 offset:128
	v_mul_f32_e32 v0, v139, v158
	v_mul_f32_e32 v0, v0, v170
	v_bfe_u32 v69, v0, 16, 1
	v_add3_u32 v0, v0, v69, s91
	flat_store_short_d16_hi v[100:101], v0 offset:192
	v_mul_f32_e32 v0, v97, v161
	v_mul_f32_e32 v0, v0, v160
	s_mov_b32 s0, 0x10000
	v_bfe_u32 v69, v0, 16, 1
	v_add_co_u32_e32 v96, vcc, s0, v66
	v_add3_u32 v0, v0, v69, s91
	s_nop 0
	v_addc_co_u32_e32 v97, vcc, 0, v67, vcc
	flat_store_short_d16_hi v[96:97], v0
	v_mul_f32_e32 v0, v113, v161
	v_mul_f32_e32 v0, v0, v168
	v_bfe_u32 v69, v0, 16, 1
	v_add3_u32 v0, v0, v69, s91
	flat_store_short_d16_hi v[96:97], v0 offset:64
	v_mul_f32_e32 v0, v130, v161
	v_mul_f32_e32 v0, v0, v169
	v_bfe_u32 v69, v0, 16, 1
	v_add3_u32 v0, v0, v69, s91
	flat_store_short_d16_hi v[96:97], v0 offset:128
	v_mul_f32_e32 v0, v143, v161
	v_mul_f32_e32 v0, v0, v170
	v_bfe_u32 v69, v0, 16, 1
	v_add3_u32 v0, v0, v69, s91
	flat_store_short_d16_hi v[96:97], v0 offset:192
	v_mul_f32_e32 v0, v95, v162
	v_mul_f32_e32 v0, v0, v160
	s_mov_b32 s0, 0x11000
	v_bfe_u32 v69, v0, 16, 1
	v_add_co_u32_e32 v96, vcc, s0, v66
	v_add3_u32 v0, v0, v69, s91
	s_nop 0
	v_addc_co_u32_e32 v97, vcc, 0, v67, vcc
	flat_store_short_d16_hi v[96:97], v0
	v_mul_f32_e32 v0, v111, v162
	v_mul_f32_e32 v0, v0, v168
	v_bfe_u32 v69, v0, 16, 1
	v_add3_u32 v0, v0, v69, s91
	flat_store_short_d16_hi v[96:97], v0 offset:64
	v_mul_f32_e32 v0, v128, v162
	v_mul_f32_e32 v0, v0, v169
	v_bfe_u32 v69, v0, 16, 1
	v_add3_u32 v0, v0, v69, s91
	flat_store_short_d16_hi v[96:97], v0 offset:128
	v_mul_f32_e32 v0, v140, v162
	v_mul_f32_e32 v0, v0, v170
	v_bfe_u32 v69, v0, 16, 1
	v_add3_u32 v0, v0, v69, s91
	flat_store_short_d16_hi v[96:97], v0 offset:192
	v_mul_f32_e32 v0, v94, v163
	v_mul_f32_e32 v0, v0, v160
	s_mov_b32 s0, 0x12000
	v_bfe_u32 v69, v0, 16, 1
	v_add_co_u32_e32 v94, vcc, s0, v66
	v_add3_u32 v0, v0, v69, s91
	s_nop 0
	v_addc_co_u32_e32 v95, vcc, 0, v67, vcc
	flat_store_short_d16_hi v[94:95], v0
	v_mul_f32_e32 v0, v109, v163
	v_mul_f32_e32 v0, v0, v168
	v_bfe_u32 v69, v0, 16, 1
	v_add3_u32 v0, v0, v69, s91
	flat_store_short_d16_hi v[94:95], v0 offset:64
	v_mul_f32_e32 v0, v125, v163
	v_mul_f32_e32 v0, v0, v169
	v_bfe_u32 v69, v0, 16, 1
	v_add3_u32 v0, v0, v69, s91
	flat_store_short_d16_hi v[94:95], v0 offset:128
	v_mul_f32_e32 v0, v138, v163
	v_mul_f32_e32 v0, v0, v170
	v_bfe_u32 v69, v0, 16, 1
	v_add3_u32 v0, v0, v69, s91
	flat_store_short_d16_hi v[94:95], v0 offset:192
	v_mul_f32_e32 v0, v92, v164
	v_mul_f32_e32 v0, v0, v160
	s_mov_b32 s0, 0x13000
	v_bfe_u32 v69, v0, 16, 1
	v_add_co_u32_e32 v94, vcc, s0, v66
	v_add3_u32 v0, v0, v69, s91
; __device__ __forceinline__ unsigned f2bf(float f) { unsigned u = __builtin_bit_cast(unsigned, f); return (u + 0x7fffu + ((u >> 16) & 1u)) >> 16; }
; __device__ __forceinline__ void attn_unit(int b, int h, int qb, const bf16_t* __restrict__ proj, const float* __restrict__ btab, float lam, float outscale,
;                                           const float* __restrict__ gain, float* o1scr, bf16_t* merged, LAS char* lds) {
;     ...
;             bf16_t* Ow = merged + (rowbase + qw + 4 * hil) * D + h * 128 + r32l;
; #pragma unroll
;             for (int r = 0; r < 16; ++r) { bf16_t* orp = Ow + (long)((r & 3) + 8 * (r >> 2)) * D;
; #pragma unroll
;                 for (int d0 = 0; d0 < 4; ++d0) orp[d0 * 32] = (bf16_t)f2bf(o[d0][r] * ssq[r] * gn[d0]); }
	s_nop 0
	v_addc_co_u32_e32 v95, vcc, 0, v67, vcc
	flat_store_short_d16_hi v[94:95], v0
	v_mul_f32_e32 v0, v106, v164
	v_mul_f32_e32 v0, v0, v168
	v_bfe_u32 v69, v0, 16, 1
	v_add3_u32 v0, v0, v69, s91
	flat_store_short_d16_hi v[94:95], v0 offset:64
	v_mul_f32_e32 v0, v123, v164
	v_mul_f32_e32 v0, v0, v169
	v_bfe_u32 v69, v0, 16, 1
	v_add3_u32 v0, v0, v69, s91
	flat_store_short_d16_hi v[94:95], v0 offset:128
	v_mul_f32_e32 v0, v137, v164
	v_mul_f32_e32 v0, v0, v170
	v_bfe_u32 v69, v0, 16, 1
	v_add3_u32 v0, v0, v69, s91
	flat_store_short_d16_hi v[94:95], v0 offset:192
	v_mul_f32_e32 v0, v93, v167
	v_mul_f32_e32 v0, v0, v160
	s_mov_b32 s0, 0x18000
	v_bfe_u32 v69, v0, 16, 1
	v_add_co_u32_e32 v92, vcc, s0, v66
	v_add3_u32 v0, v0, v69, s91
	s_nop 0
	v_addc_co_u32_e32 v93, vcc, 0, v67, vcc
	flat_store_short_d16_hi v[92:93], v0
	v_mul_f32_e32 v0, v108, v167
	v_mul_f32_e32 v0, v0, v168
	v_bfe_u32 v69, v0, 16, 1
	v_add3_u32 v0, v0, v69, s91
	flat_store_short_d16_hi v[92:93], v0 offset:64
	v_mul_f32_e32 v0, v127, v167
	v_mul_f32_e32 v0, v0, v169
	v_bfe_u32 v69, v0, 16, 1
	v_add3_u32 v0, v0, v69, s91
	flat_store_short_d16_hi v[92:93], v0 offset:128
	v_mul_f32_e32 v0, v151, v167
	v_mul_f32_e32 v0, v0, v170
	v_bfe_u32 v69, v0, 16, 1
	v_add3_u32 v0, v0, v69, s91
	flat_store_short_d16_hi v[92:93], v0 offset:192
	v_mul_f32_e32 v0, v91, v166
	v_mul_f32_e32 v0, v0, v160
	s_mov_b32 s0, 0x19000
	v_bfe_u32 v69, v0, 16, 1
	v_add_co_u32_e32 v92, vcc, s0, v66
	v_add3_u32 v0, v0, v69, s91
	s_nop 0
	v_addc_co_u32_e32 v93, vcc, 0, v67, vcc
	flat_store_short_d16_hi v[92:93], v0
	v_mul_f32_e32 v0, v105, v166
	v_mul_f32_e32 v0, v0, v168
	v_bfe_u32 v69, v0, 16, 1
	v_add3_u32 v0, v0, v69, s91
	flat_store_short_d16_hi v[92:93], v0 offset:64
	v_mul_f32_e32 v0, v124, v166
	v_mul_f32_e32 v0, v0, v169
	v_bfe_u32 v69, v0, 16, 1
	v_add3_u32 v0, v0, v69, s91
	flat_store_short_d16_hi v[92:93], v0 offset:128
	v_mul_f32_e32 v0, v150, v166
	v_mul_f32_e32 v0, v0, v170
	v_bfe_u32 v69, v0, 16, 1
	v_add3_u32 v0, v0, v69, s91
	flat_store_short_d16_hi v[92:93], v0 offset:192
	v_mul_f32_e32 v0, v90, v165
	v_mul_f32_e32 v0, v160, v0
	s_mov_b32 s0, 0x1a000
	v_bfe_u32 v69, v0, 16, 1
	v_add_co_u32_e32 v90, vcc, s0, v66
	v_add3_u32 v0, v0, v69, s91
	s_nop 0
	v_addc_co_u32_e32 v91, vcc, 0, v67, vcc
	flat_store_short_d16_hi v[90:91], v0
	v_mul_f32_e32 v0, v102, v165
	v_mul_f32_e32 v0, v0, v168
	v_bfe_u32 v69, v0, 16, 1
	v_add3_u32 v0, v0, v69, s91
	flat_store_short_d16_hi v[90:91], v0 offset:64
	v_mul_f32_e32 v0, v121, v165
	v_mul_f32_e32 v0, v0, v169
	v_bfe_u32 v69, v0, 16, 1
	v_add3_u32 v0, v0, v69, s91
	flat_store_short_d16_hi v[90:91], v0 offset:128
	v_mul_f32_e32 v0, v149, v165
	v_mul_f32_e32 v0, v0, v170
	v_bfe_u32 v69, v0, 16, 1
	v_add3_u32 v0, v0, v69, s91
	flat_store_short_d16_hi v[90:91], v0 offset:192
	v_mul_f32_e32 v0, v89, v159
	v_mul_f32_e32 v0, v160, v0
	s_mov_b32 s0, 0x1b000
	v_bfe_u32 v69, v0, 16, 1
	v_add_co_u32_e32 v66, vcc, s0, v66
	v_add3_u32 v0, v0, v69, s91
	s_nop 0
	v_addc_co_u32_e32 v67, vcc, 0, v67, vcc
	flat_store_short_d16_hi v[66:67], v0
	v_mul_f32_e32 v0, v99, v159
	v_mul_f32_e32 v0, v168, v0
	v_bfe_u32 v69, v0, 16, 1
	v_add3_u32 v0, v0, v69, s91
	flat_store_short_d16_hi v[66:67], v0 offset:64
	v_mul_f32_e32 v0, v119, v159
	v_mul_f32_e32 v0, v169, v0
	v_bfe_u32 v69, v0, 16, 1
	v_add3_u32 v0, v0, v69, s91
	flat_store_short_d16_hi v[66:67], v0 offset:128
	v_mul_f32_e32 v0, v68, v159
	v_mul_f32_e32 v0, v170, v0
	v_bfe_u32 v68, v0, 16, 1
	v_add3_u32 v0, v0, v68, s91
	flat_store_short_d16_hi v[66:67], v0 offset:192
	s_cbranch_execnz .LBB0_186
